# v23 + write-through (sc1) on the final-norm phase's 16 f32 output stores
# speedup vs baseline: 1.0058x; 1.0058x over previous
.LBB0_80:
	s_ashr_i32 s11, s10, 31
	s_lshl_b64 s[4:5], s[10:11], 11
	v_lshl_add_u64 v[22:23], v[4:5], 0, s[4:5]
	s_lshl_b64 s[4:5], s[10:11], 6
	s_add_u32 s4, s12, s4
	s_addc_u32 s5, s13, s5
	global_load_dwordx4 v[0:3], v189, s[4:5] offset:48
	global_load_dwordx4 v[10:13], v189, s[4:5] offset:32
	global_load_dwordx4 v[14:17], v189, s[4:5] offset:16
	global_load_dwordx4 v[18:21], v189, s[4:5]
	s_add_i32 s8, s10, s14
	s_ashr_i32 s9, s8, 31
	s_lshl_b64 s[4:5], s[8:9], 11
	global_load_dwordx2 v[36:37], v[22:23], off nt
	global_load_dwordx2 v[34:35], v[22:23], off offset:512 nt
	global_load_dwordx2 v[32:33], v[22:23], off offset:1024 nt
	global_load_dwordx2 v[30:31], v[22:23], off offset:1536 nt
	v_lshl_add_u64 v[22:23], v[4:5], 0, s[4:5]
	s_lshl_b64 s[4:5], s[8:9], 6
	s_add_u32 s4, s12, s4
	s_addc_u32 s5, s13, s5
	s_add_i32 s6, s16, s10
	s_ashr_i32 s7, s6, 31
	s_add_i32 s17, s8, s14
	s_waitcnt vmcnt(6)
	v_add_f32_e32 v10, v10, v11
	v_add_f32_e32 v12, v12, v13
	s_waitcnt vmcnt(4)
	v_mov_b32_e32 v24, v19
	v_mov_b32_e32 v25, v20
	v_mov_b32_e32 v19, v21
	v_mov_b32_e32 v20, v15
	v_mov_b32_e32 v21, v16
	v_mov_b32_e32 v15, v17
	v_pk_add_f32 v[18:19], v[24:25], v[18:19]
	v_pk_add_f32 v[14:15], v[20:21], v[14:15]
	v_pk_add_f32 v[18:19], v[18:19], v[18:19] op_sel:[0,1] op_sel_hi:[1,0]
	v_pk_add_f32 v[14:15], v[14:15], v[14:15] op_sel:[0,1] op_sel_hi:[1,0]
	v_mov_b32_e32 v19, v0
	v_mov_b32_e32 v15, v1
	v_mov_b32_e32 v11, v2
	v_mov_b32_e32 v13, v3
	v_pk_add_f32 v[0:1], v[18:19], v[14:15]
	v_pk_add_f32 v[2:3], v[10:11], v[12:13]
	s_nop 0
	v_pk_add_f32 v[24:25], v[0:1], v[2:3]
	global_load_dwordx4 v[0:3], v189, s[4:5] offset:48
	global_load_dwordx4 v[10:13], v189, s[4:5] offset:32
	global_load_dwordx4 v[14:17], v189, s[4:5] offset:16
	global_load_dwordx4 v[18:21], v189, s[4:5]
	s_lshl_b64 s[4:5], s[6:7], 11
	global_load_dwordx2 v[46:47], v[22:23], off nt
	global_load_dwordx2 v[44:45], v[22:23], off offset:512 nt
	global_load_dwordx2 v[42:43], v[22:23], off offset:1024 nt
	global_load_dwordx2 v[40:41], v[22:23], off offset:1536 nt
	v_lshl_add_u64 v[22:23], v[4:5], 0, s[4:5]
	s_lshl_b64 s[4:5], s[6:7], 6
	s_add_u32 s4, s12, s4
	s_addc_u32 s5, s13, s5
	s_add_i32 s17, s17, s14
	s_waitcnt vmcnt(6)
	v_add_f32_e32 v10, v10, v11
	v_add_f32_e32 v12, v12, v13
	s_waitcnt vmcnt(4)
	v_mov_b32_e32 v26, v19
	v_mov_b32_e32 v27, v20
	v_mov_b32_e32 v19, v21
	v_mov_b32_e32 v20, v15
	v_mov_b32_e32 v21, v16
	v_mov_b32_e32 v15, v17
	v_pk_add_f32 v[18:19], v[26:27], v[18:19]
	v_pk_add_f32 v[14:15], v[20:21], v[14:15]
	v_pk_add_f32 v[18:19], v[18:19], v[18:19] op_sel:[0,1] op_sel_hi:[1,0]
	v_pk_add_f32 v[14:15], v[14:15], v[14:15] op_sel:[0,1] op_sel_hi:[1,0]
	v_mov_b32_e32 v19, v0
	v_mov_b32_e32 v15, v1
	v_mov_b32_e32 v11, v2
	v_mov_b32_e32 v13, v3
	v_pk_add_f32 v[0:1], v[18:19], v[14:15]
	v_pk_add_f32 v[2:3], v[10:11], v[12:13]
	s_nop 0
	v_pk_add_f32 v[0:1], v[0:1], v[2:3]
	v_mov_b32_e32 v3, v24
	v_mov_b32_e32 v2, v0
	v_mov_b32_e32 v24, v1
	v_pk_add_f32 v[0:1], v[2:3], v[24:25]
	s_nop 0
	v_pk_fma_f32 v[0:1], v[0:1], s[26:27], v[190:191] op_sel_hi:[1,0,0]
	s_nop 0
	v_mul_f32_e32 v2, 0x4b800000, v1
	v_cmp_gt_f32_e64 s[38:39], s95, v1
	v_cmp_gt_f32_e32 vcc, s95, v0
	s_nop 0
	v_cndmask_b32_e64 v1, v1, v2, s[38:39]
	v_rsq_f32_e32 v1, v1
	s_nop 0
	v_mul_f32_e32 v2, 0x45800000, v1
	v_cndmask_b32_e64 v48, v1, v2, s[38:39]
	v_mul_f32_e32 v1, 0x4b800000, v0
	v_cndmask_b32_e32 v0, v0, v1, vcc
	v_rsq_f32_e32 v0, v0
	s_nop 0
	v_mul_f32_e32 v1, 0x45800000, v0
	v_cndmask_b32_e32 v38, v0, v1, vcc
	global_load_dwordx4 v[0:3], v189, s[4:5] offset:48
	global_load_dwordx4 v[10:13], v189, s[4:5] offset:32
	global_load_dwordx4 v[14:17], v189, s[4:5] offset:16
	global_load_dwordx4 v[18:21], v189, s[4:5]
	s_mul_i32 s4, s96, 24
	s_add_i32 s4, s4, s10
	s_ashr_i32 s5, s4, 31
	s_lshl_b64 s[18:19], s[4:5], 11
	v_lshl_add_u64 v[54:55], v[4:5], 0, s[18:19]
	s_lshl_b64 s[18:19], s[4:5], 6
	s_add_u32 s18, s12, s18
	s_addc_u32 s19, s13, s19
	s_lshl_b64 s[10:11], s[10:11], 12
	s_lshl_b64 s[8:9], s[8:9], 12
	s_lshl_b64 s[6:7], s[6:7], 12
	s_lshl_b64 s[4:5], s[4:5], 12
	s_waitcnt vmcnt(2)
	v_add_f32_e32 v10, v10, v11
	v_add_f32_e32 v12, v12, v13
	s_waitcnt vmcnt(0)
	v_mov_b32_e32 v24, v19
	v_mov_b32_e32 v25, v20
	v_mov_b32_e32 v19, v21
	v_mov_b32_e32 v20, v15
	v_mov_b32_e32 v21, v16
	v_mov_b32_e32 v15, v17
	v_pk_add_f32 v[18:19], v[24:25], v[18:19]
	v_pk_add_f32 v[14:15], v[20:21], v[14:15]
	v_pk_add_f32 v[18:19], v[18:19], v[18:19] op_sel:[0,1] op_sel_hi:[1,0]
	v_pk_add_f32 v[14:15], v[14:15], v[14:15] op_sel:[0,1] op_sel_hi:[1,0]
	v_mov_b32_e32 v19, v0
	v_mov_b32_e32 v15, v1
	v_mov_b32_e32 v11, v2
	v_mov_b32_e32 v13, v3
	v_pk_add_f32 v[0:1], v[18:19], v[14:15]
	v_pk_add_f32 v[2:3], v[10:11], v[12:13]
	global_load_dwordx2 v[24:25], v[22:23], off nt
	global_load_dwordx2 v[20:21], v[22:23], off offset:512 nt
	global_load_dwordx2 v[16:17], v[22:23], off offset:1024 nt
	global_load_dwordx2 v[10:11], v[22:23], off offset:1536 nt
	v_pk_add_f32 v[18:19], v[0:1], v[2:3]
	global_load_dwordx4 v[0:3], v189, s[18:19] offset:48
	global_load_dwordx4 v[12:15], v189, s[18:19] offset:32
	global_load_dwordx4 v[26:29], v189, s[18:19] offset:16
	global_load_dwordx4 v[50:53], v189, s[18:19]
	s_waitcnt vmcnt(2)
	v_add_f32_e32 v12, v12, v13
	v_add_f32_e32 v14, v14, v15
	s_waitcnt vmcnt(0)
	v_mov_b32_e32 v22, v51
	v_mov_b32_e32 v23, v52
	v_mov_b32_e32 v51, v53
	v_pk_add_f32 v[22:23], v[22:23], v[50:51]
	v_mov_b32_e32 v50, v27
	v_mov_b32_e32 v51, v28
	v_mov_b32_e32 v27, v29
	v_pk_add_f32 v[26:27], v[50:51], v[26:27]
	v_pk_add_f32 v[22:23], v[22:23], v[22:23] op_sel:[0,1] op_sel_hi:[1,0]
	v_pk_add_f32 v[26:27], v[26:27], v[26:27] op_sel:[0,1] op_sel_hi:[1,0]
	v_mov_b32_e32 v23, v0
	v_mov_b32_e32 v27, v1
	v_mov_b32_e32 v13, v2
	v_mov_b32_e32 v15, v3
	v_pk_add_f32 v[0:1], v[22:23], v[26:27]
	v_pk_add_f32 v[2:3], v[12:13], v[14:15]
	v_lshlrev_b32_e32 v52, 16, v36
	v_pk_add_f32 v[0:1], v[0:1], v[2:3]
	v_mov_b32_e32 v3, v18
	v_mov_b32_e32 v2, v0
	v_mov_b32_e32 v18, v1
	v_pk_add_f32 v[0:1], v[2:3], v[18:19]
	v_mov_b64_e32 v[2:3], s[22:23]
	v_pk_fma_f32 v[0:1], v[0:1], s[26:27], v[2:3] op_sel_hi:[1,0,0]
	global_load_dwordx2 v[26:27], v[54:55], off nt
	global_load_dwordx2 v[22:23], v[54:55], off offset:512 nt
	global_load_dwordx2 v[18:19], v[54:55], off offset:1024 nt
	global_load_dwordx2 v[14:15], v[54:55], off offset:1536 nt
	v_mul_f32_e32 v2, 0x4b800000, v1
	v_cmp_gt_f32_e64 s[38:39], s95, v1
	v_cmp_gt_f32_e32 vcc, s95, v0
	v_and_b32_e32 v53, 0xffff0000, v36
	v_cndmask_b32_e64 v1, v1, v2, s[38:39]
	v_rsq_f32_e32 v1, v1
	v_lshlrev_b32_e32 v36, 16, v37
	v_and_b32_e32 v37, 0xffff0000, v37
	v_pk_mul_f32 v[52:53], v[48:49], v[52:53] op_sel_hi:[0,1]
	v_mul_f32_e32 v2, 0x45800000, v1
	v_cndmask_b32_e64 v28, v1, v2, s[38:39]
	v_mul_f32_e32 v1, 0x4b800000, v0
	v_cndmask_b32_e32 v0, v0, v1, vcc
	v_rsq_f32_e32 v0, v0
	v_pk_mul_f32 v[36:37], v[48:49], v[36:37] op_sel_hi:[0,1]
	v_lshl_add_u64 v[50:51], v[6:7], 0, s[10:11]
	s_add_i32 s10, s17, s14
	v_mul_f32_e32 v1, 0x45800000, v0
	v_cndmask_b32_e32 v12, v0, v1, vcc
	global_load_dwordx4 v[0:3], v[8:9], off
	s_cmpk_gt_i32 s10, 0x7fff
	s_waitcnt vmcnt(0)
	v_pk_mul_f32 v[2:3], v[36:37], v[2:3]
	v_pk_mul_f32 v[0:1], v[52:53], v[0:1]
	global_store_dwordx4 v[50:51], v[0:3], off sc1
	global_load_dwordx4 v[0:3], v[8:9], off offset:1024
	v_lshlrev_b32_e32 v36, 16, v34
	v_and_b32_e32 v37, 0xffff0000, v34
	v_lshlrev_b32_e32 v34, 16, v35
	v_and_b32_e32 v35, 0xffff0000, v35
	v_pk_mul_f32 v[34:35], v[48:49], v[34:35] op_sel_hi:[0,1]
	v_pk_mul_f32 v[36:37], v[48:49], v[36:37] op_sel_hi:[0,1]
	s_waitcnt vmcnt(0)
	v_pk_mul_f32 v[0:1], v[36:37], v[0:1]
	v_pk_mul_f32 v[2:3], v[34:35], v[2:3]
	global_store_dwordx4 v[50:51], v[0:3], off offset:1024 sc1
	global_load_dwordx4 v[0:3], v[8:9], off offset:2048
	v_lshlrev_b32_e32 v34, 16, v32
	v_and_b32_e32 v35, 0xffff0000, v32
	v_lshlrev_b32_e32 v32, 16, v33
	v_and_b32_e32 v33, 0xffff0000, v33
	v_pk_mul_f32 v[32:33], v[48:49], v[32:33] op_sel_hi:[0,1]
	v_pk_mul_f32 v[34:35], v[48:49], v[34:35] op_sel_hi:[0,1]
	s_waitcnt vmcnt(0)
	v_pk_mul_f32 v[0:1], v[34:35], v[0:1]
	v_pk_mul_f32 v[2:3], v[32:33], v[2:3]
	global_store_dwordx4 v[50:51], v[0:3], off offset:2048 sc1
	global_load_dwordx4 v[0:3], v[8:9], off offset:3072
	v_lshlrev_b32_e32 v32, 16, v30
	v_and_b32_e32 v33, 0xffff0000, v30
	v_lshlrev_b32_e32 v30, 16, v31
	v_and_b32_e32 v31, 0xffff0000, v31
	v_pk_mul_f32 v[30:31], v[48:49], v[30:31] op_sel_hi:[0,1]
	v_pk_mul_f32 v[32:33], v[48:49], v[32:33] op_sel_hi:[0,1]
	v_lshlrev_b32_e32 v34, 16, v47
	v_and_b32_e32 v35, 0xffff0000, v47
	v_pk_mul_f32 v[34:35], v[38:39], v[34:35] op_sel_hi:[0,1]
	s_waitcnt vmcnt(0)
	v_pk_mul_f32 v[0:1], v[32:33], v[0:1]
	v_pk_mul_f32 v[2:3], v[30:31], v[2:3]
	global_store_dwordx4 v[50:51], v[0:3], off offset:3072 sc1
	global_load_dwordx4 v[0:3], v[8:9], off
	v_lshlrev_b32_e32 v32, 16, v46
	v_and_b32_e32 v33, 0xffff0000, v46
	v_pk_mul_f32 v[32:33], v[38:39], v[32:33] op_sel_hi:[0,1]
	v_lshl_add_u64 v[30:31], v[6:7], 0, s[8:9]
	s_waitcnt vmcnt(0)
	v_pk_mul_f32 v[0:1], v[32:33], v[0:1]
	v_pk_mul_f32 v[2:3], v[34:35], v[2:3]
	global_store_dwordx4 v[30:31], v[0:3], off sc1
	global_load_dwordx4 v[0:3], v[8:9], off offset:1024
	v_lshlrev_b32_e32 v32, 16, v44
	v_and_b32_e32 v33, 0xffff0000, v44
	v_lshlrev_b32_e32 v34, 16, v45
	v_and_b32_e32 v35, 0xffff0000, v45
	v_pk_mul_f32 v[34:35], v[38:39], v[34:35] op_sel_hi:[0,1]
	v_pk_mul_f32 v[32:33], v[38:39], v[32:33] op_sel_hi:[0,1]
	s_waitcnt vmcnt(0)
	v_pk_mul_f32 v[0:1], v[32:33], v[0:1]
	v_pk_mul_f32 v[2:3], v[34:35], v[2:3]
	global_store_dwordx4 v[30:31], v[0:3], off offset:1024 sc1
	global_load_dwordx4 v[0:3], v[8:9], off offset:2048
	v_lshlrev_b32_e32 v32, 16, v42
	v_and_b32_e32 v33, 0xffff0000, v42
	v_lshlrev_b32_e32 v34, 16, v43
	v_and_b32_e32 v35, 0xffff0000, v43
	v_pk_mul_f32 v[34:35], v[38:39], v[34:35] op_sel_hi:[0,1]
	v_pk_mul_f32 v[32:33], v[38:39], v[32:33] op_sel_hi:[0,1]
	s_waitcnt vmcnt(0)
	v_pk_mul_f32 v[0:1], v[32:33], v[0:1]
	v_pk_mul_f32 v[2:3], v[34:35], v[2:3]
	global_store_dwordx4 v[30:31], v[0:3], off offset:2048 sc1
	global_load_dwordx4 v[0:3], v[8:9], off offset:3072
	v_lshlrev_b32_e32 v32, 16, v40
	v_and_b32_e32 v33, 0xffff0000, v40
	v_lshlrev_b32_e32 v34, 16, v41
	v_and_b32_e32 v35, 0xffff0000, v41
	v_pk_mul_f32 v[34:35], v[38:39], v[34:35] op_sel_hi:[0,1]
	v_pk_mul_f32 v[32:33], v[38:39], v[32:33] op_sel_hi:[0,1]
	s_waitcnt vmcnt(0)
	v_pk_mul_f32 v[0:1], v[32:33], v[0:1]
	v_pk_mul_f32 v[2:3], v[34:35], v[2:3]
	global_store_dwordx4 v[30:31], v[0:3], off offset:3072 sc1
	global_load_dwordx4 v[30:33], v[8:9], off
	s_nop 0
	v_lshlrev_b32_e32 v2, 16, v24
	v_and_b32_e32 v3, 0xffff0000, v24
	v_lshlrev_b32_e32 v24, 16, v25
	v_and_b32_e32 v25, 0xffff0000, v25
	v_pk_mul_f32 v[24:25], v[28:29], v[24:25] op_sel_hi:[0,1]
	v_pk_mul_f32 v[2:3], v[28:29], v[2:3] op_sel_hi:[0,1]
	v_lshl_add_u64 v[0:1], v[6:7], 0, s[6:7]
	s_waitcnt vmcnt(0)
	v_pk_mul_f32 v[30:31], v[2:3], v[30:31]
	v_pk_mul_f32 v[32:33], v[24:25], v[32:33]
	global_store_dwordx4 v[0:1], v[30:33], off sc1
	global_load_dwordx4 v[30:33], v[8:9], off offset:1024
	v_lshlrev_b32_e32 v2, 16, v20
	v_and_b32_e32 v3, 0xffff0000, v20
	v_lshlrev_b32_e32 v20, 16, v21
	v_and_b32_e32 v21, 0xffff0000, v21
	v_pk_mul_f32 v[20:21], v[28:29], v[20:21] op_sel_hi:[0,1]
	v_pk_mul_f32 v[2:3], v[28:29], v[2:3] op_sel_hi:[0,1]
	s_waitcnt vmcnt(0)
	v_pk_mul_f32 v[30:31], v[2:3], v[30:31]
	v_pk_mul_f32 v[32:33], v[20:21], v[32:33]
	global_store_dwordx4 v[0:1], v[30:33], off offset:1024 sc1
	global_load_dwordx4 v[30:33], v[8:9], off offset:2048
	v_lshlrev_b32_e32 v2, 16, v16
	v_and_b32_e32 v3, 0xffff0000, v16
	v_lshlrev_b32_e32 v16, 16, v17
	v_and_b32_e32 v17, 0xffff0000, v17
	v_pk_mul_f32 v[16:17], v[28:29], v[16:17] op_sel_hi:[0,1]
	v_pk_mul_f32 v[2:3], v[28:29], v[2:3] op_sel_hi:[0,1]
	v_lshlrev_b32_e32 v20, 16, v27
	v_and_b32_e32 v21, 0xffff0000, v27
	v_pk_mul_f32 v[20:21], v[12:13], v[20:21] op_sel_hi:[0,1]
	s_waitcnt vmcnt(0)
	v_pk_mul_f32 v[30:31], v[2:3], v[30:31]
	v_pk_mul_f32 v[32:33], v[16:17], v[32:33]
	global_store_dwordx4 v[0:1], v[30:33], off offset:2048 sc1
	global_load_dwordx4 v[30:33], v[8:9], off offset:3072
	v_lshlrev_b32_e32 v2, 16, v10
	v_and_b32_e32 v3, 0xffff0000, v10
	v_lshlrev_b32_e32 v10, 16, v11
	v_and_b32_e32 v11, 0xffff0000, v11
	v_pk_mul_f32 v[10:11], v[28:29], v[10:11] op_sel_hi:[0,1]
	v_pk_mul_f32 v[2:3], v[28:29], v[2:3] op_sel_hi:[0,1]
	v_lshlrev_b32_e32 v16, 16, v26
	v_and_b32_e32 v17, 0xffff0000, v26
	v_pk_mul_f32 v[16:17], v[12:13], v[16:17] op_sel_hi:[0,1]
	s_waitcnt vmcnt(0)
	v_pk_mul_f32 v[28:29], v[2:3], v[30:31]
	v_pk_mul_f32 v[30:31], v[10:11], v[32:33]
	global_store_dwordx4 v[0:1], v[28:31], off offset:3072 sc1
	global_load_dwordx4 v[0:3], v[8:9], off
	v_lshl_add_u64 v[10:11], v[6:7], 0, s[4:5]
	s_waitcnt vmcnt(0)
	v_pk_mul_f32 v[0:1], v[16:17], v[0:1]
	v_pk_mul_f32 v[2:3], v[20:21], v[2:3]
	global_store_dwordx4 v[10:11], v[0:3], off sc1
	global_load_dwordx4 v[0:3], v[8:9], off offset:1024
	v_lshlrev_b32_e32 v16, 16, v22
	v_and_b32_e32 v17, 0xffff0000, v22
	v_lshlrev_b32_e32 v20, 16, v23
	v_and_b32_e32 v21, 0xffff0000, v23
	v_pk_mul_f32 v[20:21], v[12:13], v[20:21] op_sel_hi:[0,1]
	v_pk_mul_f32 v[16:17], v[12:13], v[16:17] op_sel_hi:[0,1]
	s_waitcnt vmcnt(0)
	v_pk_mul_f32 v[0:1], v[16:17], v[0:1]
	v_pk_mul_f32 v[2:3], v[20:21], v[2:3]
	global_store_dwordx4 v[10:11], v[0:3], off offset:1024 sc1
	global_load_dwordx4 v[0:3], v[8:9], off offset:2048
	v_lshlrev_b32_e32 v16, 16, v18
	v_and_b32_e32 v17, 0xffff0000, v18
	v_lshlrev_b32_e32 v18, 16, v19
	v_and_b32_e32 v19, 0xffff0000, v19
	v_pk_mul_f32 v[18:19], v[12:13], v[18:19] op_sel_hi:[0,1]
	v_pk_mul_f32 v[16:17], v[12:13], v[16:17] op_sel_hi:[0,1]
	s_waitcnt vmcnt(0)
	v_pk_mul_f32 v[0:1], v[16:17], v[0:1]
	v_pk_mul_f32 v[2:3], v[18:19], v[2:3]
	global_store_dwordx4 v[10:11], v[0:3], off offset:2048 sc1
	global_load_dwordx4 v[0:3], v[8:9], off offset:3072
	v_lshlrev_b32_e32 v16, 16, v14
	v_and_b32_e32 v17, 0xffff0000, v14
	v_lshlrev_b32_e32 v14, 16, v15
	v_and_b32_e32 v15, 0xffff0000, v15
	v_pk_mul_f32 v[14:15], v[12:13], v[14:15] op_sel_hi:[0,1]
	v_pk_mul_f32 v[12:13], v[12:13], v[16:17] op_sel_hi:[0,1]
	s_waitcnt vmcnt(0)
	v_pk_mul_f32 v[0:1], v[12:13], v[0:1]
	v_pk_mul_f32 v[2:3], v[14:15], v[2:3]
	global_store_dwordx4 v[10:11], v[0:3], off offset:3072 sc1
	s_cbranch_scc0 .LBB0_80
